# KV epilogue: the seven later row-statistics vectors taken from the registers of the up-front prefetch instead of re-loaded behind each output store
# speedup vs baseline: 1.0021x; 1.0021x over previous
; DI void rope4(f32x4& v0, f32x4& v1, const float* tab_row, int fq) {
;     const f32x4 cs0 = *(const f32x4*)(tab_row + 8 * fq), cs1 = *(const f32x4*)(tab_row + 8 * fq + 4);
;     const float c[4] = {cs0[0], cs0[2], cs1[0], cs1[2]}, s[4] = {cs0[1], cs0[3], cs1[1], cs1[3]};
;     f32x4 a, b;
; #pragma unroll
;     for (int j = 0; j < 4; ++j) { a[j] = v0[j] * c[j] - v1[j] * s[j]; b[j] = v0[j] * s[j] + v1[j] * c[j]; }
;     v0 = a; v1 = b;
; }
;     DI void operator()(const f32x4 (&acc)[2][2][4][2], const pg8::Unit& u, int wr, int wc, int fr, int fq) const {
;         asm volatile("" : "+v"(fr), "+v"(fq));
;         const int row0 = u.pm * 256 + wr * 64 + fr, col0 = wc * 32 + 8 * fq;
;         bf16_t* dst = u.pn == 0 ? Kb : Vb;
; #pragma unroll
;         for (int ai = 0; ai < 2; ++ai)
; #pragma unroll
;             for (int m = 0; m < 4; ++m) {
;                 const int row = row0 + ai * 128 + m * 16; const f32x4 p = *(const f32x4*)(SSQ + (size_t)row * 4);
;                 const float rs = __builtin_amdgcn_rsqf(((p[0] + p[1]) + (p[2] + p[3])) * (1.0f / 128.0f) + EPS);
; #pragma unroll
;                 for (int bj = 0; bj < 2; ++bj) { f32x4 v0 = acc[ai][bj][m][0] * rs, v1 = acc[ai][bj][m][1] * rs;
;                     if (u.pn == 0 && (wc & 1)) {
;                         if (fq < 2) { const u32x2 a = *(const u32x2*)(H + (size_t)row * HP + C_KR + 4 * fq), b = *(const u32x2*)(H + (size_t)row * HP + C_KR + 8 + 4 * fq);
;                             v0 = (f32x4){__uint_as_float(a.x << 16), __uint_as_float(a.x & 0xffff0000u), __uint_as_float(a.y << 16), __uint_as_float(a.y & 0xffff0000u)};
;                             v1 = (f32x4){__uint_as_float(b.x << 16), __uint_as_float(b.x & 0xffff0000u), __uint_as_float(b.y << 16), __uint_as_float(b.y & 0xffff0000u)};
;                             rope4(v0, v1, ROPE16 + (size_t)row * 16, fq); }
;                         else { v0 = (f32x4){0.f, 0.f, 0.f, 0.f}; v1 = v0; }
;                     }
;                     u32x4 w; w.x = pk2(v0[0], v0[1]); w.y = pk2(v0[2], v0[3]); w.z = pk2(v1[0], v1[1]); w.w = pk2(v1[2], v1[3]);
;                     *(u32x4*)(dst + (size_t)row * 256 + bj * 128 + col0) = w; }
;                 asm volatile("" ::: "memory");
;             }
;     }
.LBB0_895:
	s_or_b64 exec, exec, s[2:3]
	v_cvt_pk_bf16_f32 v116, v116, v117
	v_cvt_pk_bf16_f32 v117, v120, v121
	v_cvt_pk_bf16_f32 v118, v118, v119
	v_cvt_pk_bf16_f32 v119, v114, v115
	global_store_dwordx4 v[150:151], v[116:119], off offset:256
	s_nop 1
	v_add_u32_e32 v116, 16, v140
	v_ashrrev_i32_e32 v117, 31, v116
	v_lshl_add_u64 v[114:115], v[116:117], 4, s[28:29]
	s_nop 1
	v_mov_b32_e32 v118, v220
	v_mov_b32_e32 v119, v221
	v_mov_b32_e32 v120, v222
	v_mov_b32_e32 v121, v223
	v_lshlrev_b64 v[124:125], 6, v[116:117]
	s_nop 0
	v_mov_b32_e32 v114, v119
	v_mov_b32_e32 v115, v120
	v_mov_b32_e32 v119, v121
	v_pk_add_f32 v[114:115], v[114:115], v[118:119]
	v_mad_i64_i32 v[120:121], s[2:3], v116, s73, 0
	v_add_f32_e32 v114, v114, v115
	v_fmamk_f32 v114, v114, 0x3c000000, v202
	v_rsq_f32_e32 v114, v114
	s_nop 0
	v_pk_mul_f32 v[106:107], v[106:107], v[114:115] op_sel_hi:[1,0]
	v_pk_mul_f32 v[118:119], v[112:113], v[114:115] op_sel_hi:[1,0]
	v_pk_mul_f32 v[126:127], v[110:111], v[114:115] op_sel_hi:[1,0]
	v_pk_mul_f32 v[108:109], v[108:109], v[114:115] op_sel_hi:[1,0]
	v_cndmask_b32_e32 v110, 0, v106, vcc
	v_cndmask_b32_e32 v111, 0, v107, vcc
	v_lshl_add_u64 v[106:107], s[26:27], 0, v[120:121]
	v_lshl_add_u64 v[120:121], s[22:23], 0, v[124:125]
	v_cndmask_b32_e32 v112, 0, v108, vcc
	v_cndmask_b32_e32 v113, 0, v109, vcc
	v_cndmask_b32_e32 v108, 0, v126, vcc
	v_cndmask_b32_e32 v109, 0, v127, vcc
	v_cndmask_b32_e32 v118, 0, v118, vcc
	v_cndmask_b32_e32 v119, 0, v119, vcc
	v_lshl_add_u64 v[106:107], v[138:139], 1, v[106:107]
	v_lshl_add_u64 v[120:121], v[136:137], 2, v[120:121]
	s_and_saveexec_b64 s[2:3], s[18:19]
	v_readlane_b32 s55, v254, 53
	v_readlane_b32 s88, v254, 54
	s_movk_i32 s82, 0x210
	s_mov_b32 s83, 0xc2fc0000
	s_mov_b64 s[90:91], 0x100000
	s_mov_b64 s[52:53], 0x8000
	s_cbranch_execz .LBB0_897
	global_load_dwordx2 v[112:113], v[106:107], off offset:768
	global_load_dwordx2 v[118:119], v[106:107], off offset:784
	global_load_dwordx4 v[108:111], v[120:121], off
	global_load_dwordx4 v[124:127], v[120:121], off offset:16
	s_waitcnt vmcnt(3)
	v_lshlrev_b32_e32 v115, 16, v113
	s_waitcnt vmcnt(2)
	v_lshlrev_b32_e32 v141, 16, v119
	s_waitcnt vmcnt(1)
	v_mov_b32_e32 v144, v109
	v_mov_b32_e32 v145, v111
	v_mov_b32_e32 v109, v110
	v_and_b32_e32 v111, 0xffff0000, v113
	v_and_b32_e32 v110, 0xffff0000, v119
	v_lshlrev_b32_e32 v142, 16, v118
	v_and_b32_e32 v143, 0xffff0000, v118
	s_waitcnt vmcnt(0)
	v_pk_mul_f32 v[150:151], v[126:127], v[110:111] op_sel:[0,1] op_sel_hi:[1,0]
	v_pk_mul_f32 v[110:111], v[126:127], v[110:111]
	v_lshlrev_b32_e32 v128, 16, v112
	v_and_b32_e32 v129, 0xffff0000, v112
	v_pk_mul_f32 v[112:113], v[108:109], v[142:143]
	v_pk_mul_f32 v[118:119], v[144:145], v[142:143]
	v_mul_f32_e32 v142, v124, v115
	v_mul_f32_e32 v146, v125, v141
	v_mul_f32_e32 v148, v125, v115
	v_mul_f32_e32 v124, v124, v141
	v_mov_b32_e32 v143, v150
	v_mov_b32_e32 v147, v151
	v_mov_b32_e32 v149, v111
	v_mov_b32_e32 v125, v110
	v_pk_fma_f32 v[108:109], v[108:109], v[128:129], v[118:119] neg_lo:[0,0,1] neg_hi:[0,0,1]
	v_pk_fma_f32 v[110:111], v[144:145], v[128:129], v[112:113]
	v_pk_add_f32 v[118:119], v[142:143], v[146:147] neg_lo:[0,1] neg_hi:[0,1]
	v_pk_add_f32 v[112:113], v[148:149], v[124:125]

; DI void rope4(f32x4& v0, f32x4& v1, const float* tab_row, int fq) {
;     const f32x4 cs0 = *(const f32x4*)(tab_row + 8 * fq), cs1 = *(const f32x4*)(tab_row + 8 * fq + 4);
;     const float c[4] = {cs0[0], cs0[2], cs1[0], cs1[2]}, s[4] = {cs0[1], cs0[3], cs1[1], cs1[3]};
;     f32x4 a, b;
; #pragma unroll
;     for (int j = 0; j < 4; ++j) { a[j] = v0[j] * c[j] - v1[j] * s[j]; b[j] = v0[j] * s[j] + v1[j] * c[j]; }
;     v0 = a; v1 = b;
; }
;     DI void operator()(const f32x4 (&acc)[2][2][4][2], const pg8::Unit& u, int wr, int wc, int fr, int fq) const {
;         asm volatile("" : "+v"(fr), "+v"(fq));
;         const int row0 = u.pm * 256 + wr * 64 + fr, col0 = wc * 32 + 8 * fq;
;         bf16_t* dst = u.pn == 0 ? Kb : Vb;
; #pragma unroll
;         for (int ai = 0; ai < 2; ++ai)
; #pragma unroll
;             for (int m = 0; m < 4; ++m) {
;                 const int row = row0 + ai * 128 + m * 16; const f32x4 p = *(const f32x4*)(SSQ + (size_t)row * 4);
;                 const float rs = __builtin_amdgcn_rsqf(((p[0] + p[1]) + (p[2] + p[3])) * (1.0f / 128.0f) + EPS);
; #pragma unroll
;                 for (int bj = 0; bj < 2; ++bj) { f32x4 v0 = acc[ai][bj][m][0] * rs, v1 = acc[ai][bj][m][1] * rs;
;                     if (u.pn == 0 && (wc & 1)) {
;                         if (fq < 2) { const u32x2 a = *(const u32x2*)(H + (size_t)row * HP + C_KR + 4 * fq), b = *(const u32x2*)(H + (size_t)row * HP + C_KR + 8 + 4 * fq);
;                             v0 = (f32x4){__uint_as_float(a.x << 16), __uint_as_float(a.x & 0xffff0000u), __uint_as_float(a.y << 16), __uint_as_float(a.y & 0xffff0000u)};
;                             v1 = (f32x4){__uint_as_float(b.x << 16), __uint_as_float(b.x & 0xffff0000u), __uint_as_float(b.y << 16), __uint_as_float(b.y & 0xffff0000u)};
;                             rope4(v0, v1, ROPE16 + (size_t)row * 16, fq); }
;                         else { v0 = (f32x4){0.f, 0.f, 0.f, 0.f}; v1 = v0; }
;                     }
;                     u32x4 w; w.x = pk2(v0[0], v0[1]); w.y = pk2(v0[2], v0[3]); w.z = pk2(v1[0], v1[1]); w.w = pk2(v1[2], v1[3]);
;                     *(u32x4*)(dst + (size_t)row * 256 + bj * 128 + col0) = w; }
;                 asm volatile("" ::: "memory");
;             }
;     }
.LBB0_899:
	s_or_b64 exec, exec, s[2:3]
	v_cvt_pk_bf16_f32 v100, v100, v101
	v_cvt_pk_bf16_f32 v101, v104, v105
	v_cvt_pk_bf16_f32 v102, v102, v103
	v_cvt_pk_bf16_f32 v103, v98, v99
	global_store_dwordx4 v[116:117], v[100:103], off offset:256
	s_nop 1
	v_add_u32_e32 v100, 32, v140
	v_ashrrev_i32_e32 v101, 31, v100
	v_lshl_add_u64 v[98:99], v[100:101], 4, s[28:29]
	s_nop 1
	v_mov_b32_e32 v102, v224
	v_mov_b32_e32 v103, v225
	v_mov_b32_e32 v104, v226
	v_mov_b32_e32 v105, v227
	v_lshlrev_b64 v[106:107], 6, v[100:101]
	s_nop 0
	v_mov_b32_e32 v98, v103
	v_mov_b32_e32 v99, v104
	v_mov_b32_e32 v103, v105
	v_pk_add_f32 v[98:99], v[98:99], v[102:103]
	v_mad_i64_i32 v[104:105], s[2:3], v100, s73, 0
	v_add_f32_e32 v98, v98, v99
	v_fmamk_f32 v98, v98, 0x3c000000, v202
	v_rsq_f32_e32 v98, v98
	s_nop 0
	v_pk_mul_f32 v[90:91], v[90:91], v[98:99] op_sel_hi:[1,0]
	v_pk_mul_f32 v[102:103], v[96:97], v[98:99] op_sel_hi:[1,0]
	v_pk_mul_f32 v[108:109], v[94:95], v[98:99] op_sel_hi:[1,0]
	v_pk_mul_f32 v[92:93], v[92:93], v[98:99] op_sel_hi:[1,0]
	v_cndmask_b32_e32 v94, 0, v90, vcc
	v_cndmask_b32_e32 v95, 0, v91, vcc
	v_lshl_add_u64 v[90:91], s[26:27], 0, v[104:105]
	v_lshl_add_u64 v[104:105], s[22:23], 0, v[106:107]
	v_cndmask_b32_e32 v96, 0, v92, vcc
	v_cndmask_b32_e32 v97, 0, v93, vcc
	v_cndmask_b32_e32 v92, 0, v108, vcc
	v_cndmask_b32_e32 v93, 0, v109, vcc
	v_cndmask_b32_e32 v102, 0, v102, vcc
	v_cndmask_b32_e32 v103, 0, v103, vcc
	v_lshl_add_u64 v[90:91], v[138:139], 1, v[90:91]
	v_lshl_add_u64 v[104:105], v[136:137], 2, v[104:105]
	s_and_saveexec_b64 s[2:3], s[18:19]
	s_cbranch_execz .LBB0_901
	global_load_dwordx2 v[96:97], v[90:91], off offset:768
	global_load_dwordx2 v[102:103], v[90:91], off offset:784
	global_load_dwordx4 v[92:95], v[104:105], off
	global_load_dwordx4 v[106:109], v[104:105], off offset:16
	s_waitcnt vmcnt(3)
	v_lshlrev_b32_e32 v99, 16, v97
	s_waitcnt vmcnt(2)
	v_lshlrev_b32_e32 v117, 16, v103
	s_waitcnt vmcnt(1)
	v_mov_b32_e32 v114, v93
	v_mov_b32_e32 v115, v95
	v_mov_b32_e32 v93, v94
	v_and_b32_e32 v95, 0xffff0000, v97
	v_and_b32_e32 v94, 0xffff0000, v103
	v_lshlrev_b32_e32 v112, 16, v102
	v_and_b32_e32 v113, 0xffff0000, v102
	s_waitcnt vmcnt(0)
	v_pk_mul_f32 v[120:121], v[108:109], v[94:95] op_sel:[0,1] op_sel_hi:[1,0]
	v_pk_mul_f32 v[94:95], v[108:109], v[94:95]
	v_lshlrev_b32_e32 v110, 16, v96
	v_and_b32_e32 v111, 0xffff0000, v96
	v_pk_mul_f32 v[96:97], v[92:93], v[112:113]
	v_pk_mul_f32 v[102:103], v[114:115], v[112:113]
	v_mul_f32_e32 v112, v106, v99
	v_mul_f32_e32 v116, v107, v117
	v_mul_f32_e32 v118, v107, v99
	v_mul_f32_e32 v106, v106, v117
	v_mov_b32_e32 v113, v120
	v_mov_b32_e32 v117, v121
	v_mov_b32_e32 v119, v95
	v_mov_b32_e32 v107, v94
	v_pk_fma_f32 v[92:93], v[92:93], v[110:111], v[102:103] neg_lo:[0,0,1] neg_hi:[0,0,1]
	v_pk_fma_f32 v[94:95], v[114:115], v[110:111], v[96:97]
	v_pk_add_f32 v[102:103], v[112:113], v[116:117] neg_lo:[0,1] neg_hi:[0,1]
	v_pk_add_f32 v[96:97], v[118:119], v[106:107]

; DI void rope4(f32x4& v0, f32x4& v1, const float* tab_row, int fq) {
;     const f32x4 cs0 = *(const f32x4*)(tab_row + 8 * fq), cs1 = *(const f32x4*)(tab_row + 8 * fq + 4);
;     const float c[4] = {cs0[0], cs0[2], cs1[0], cs1[2]}, s[4] = {cs0[1], cs0[3], cs1[1], cs1[3]};
;     f32x4 a, b;
; #pragma unroll
;     for (int j = 0; j < 4; ++j) { a[j] = v0[j] * c[j] - v1[j] * s[j]; b[j] = v0[j] * s[j] + v1[j] * c[j]; }
;     v0 = a; v1 = b;
; }
;     DI void operator()(const f32x4 (&acc)[2][2][4][2], const pg8::Unit& u, int wr, int wc, int fr, int fq) const {
;         asm volatile("" : "+v"(fr), "+v"(fq));
;         const int row0 = u.pm * 256 + wr * 64 + fr, col0 = wc * 32 + 8 * fq;
;         bf16_t* dst = u.pn == 0 ? Kb : Vb;
; #pragma unroll
;         for (int ai = 0; ai < 2; ++ai)
; #pragma unroll
;             for (int m = 0; m < 4; ++m) {
;                 const int row = row0 + ai * 128 + m * 16; const f32x4 p = *(const f32x4*)(SSQ + (size_t)row * 4);
;                 const float rs = __builtin_amdgcn_rsqf(((p[0] + p[1]) + (p[2] + p[3])) * (1.0f / 128.0f) + EPS);
; #pragma unroll
;                 for (int bj = 0; bj < 2; ++bj) { f32x4 v0 = acc[ai][bj][m][0] * rs, v1 = acc[ai][bj][m][1] * rs;
;                     if (u.pn == 0 && (wc & 1)) {
;                         if (fq < 2) { const u32x2 a = *(const u32x2*)(H + (size_t)row * HP + C_KR + 4 * fq), b = *(const u32x2*)(H + (size_t)row * HP + C_KR + 8 + 4 * fq);
;                             v0 = (f32x4){__uint_as_float(a.x << 16), __uint_as_float(a.x & 0xffff0000u), __uint_as_float(a.y << 16), __uint_as_float(a.y & 0xffff0000u)};
;                             v1 = (f32x4){__uint_as_float(b.x << 16), __uint_as_float(b.x & 0xffff0000u), __uint_as_float(b.y << 16), __uint_as_float(b.y & 0xffff0000u)};
;                             rope4(v0, v1, ROPE16 + (size_t)row * 16, fq); }
;                         else { v0 = (f32x4){0.f, 0.f, 0.f, 0.f}; v1 = v0; }
;                     }
;                     u32x4 w; w.x = pk2(v0[0], v0[1]); w.y = pk2(v0[2], v0[3]); w.z = pk2(v1[0], v1[1]); w.w = pk2(v1[2], v1[3]);
;                     *(u32x4*)(dst + (size_t)row * 256 + bj * 128 + col0) = w; }
;                 asm volatile("" ::: "memory");
;             }
;     }
.LBB0_903:
	s_or_b64 exec, exec, s[2:3]
	v_cvt_pk_bf16_f32 v84, v84, v85
	v_cvt_pk_bf16_f32 v85, v88, v89
	v_cvt_pk_bf16_f32 v86, v86, v87
	v_cvt_pk_bf16_f32 v87, v82, v83
	global_store_dwordx4 v[100:101], v[84:87], off offset:256
	s_nop 1
	v_add_u32_e32 v84, 48, v140
	v_ashrrev_i32_e32 v85, 31, v84
	v_lshl_add_u64 v[82:83], v[84:85], 4, s[28:29]
	s_nop 1
	v_mov_b32_e32 v86, v228
	v_mov_b32_e32 v87, v229
	v_mov_b32_e32 v88, v230
	v_mov_b32_e32 v89, v231
	v_lshlrev_b64 v[90:91], 6, v[84:85]
	s_nop 0
	v_mov_b32_e32 v82, v87
	v_mov_b32_e32 v83, v88
	v_mov_b32_e32 v87, v89
	v_pk_add_f32 v[82:83], v[82:83], v[86:87]
	v_mad_i64_i32 v[88:89], s[2:3], v84, s73, 0
	v_add_f32_e32 v82, v82, v83
	v_fmamk_f32 v82, v82, 0x3c000000, v202
	v_rsq_f32_e32 v82, v82
	s_nop 0
	v_pk_mul_f32 v[74:75], v[74:75], v[82:83] op_sel_hi:[1,0]
	v_pk_mul_f32 v[86:87], v[80:81], v[82:83] op_sel_hi:[1,0]
	v_pk_mul_f32 v[92:93], v[78:79], v[82:83] op_sel_hi:[1,0]
	v_pk_mul_f32 v[76:77], v[76:77], v[82:83] op_sel_hi:[1,0]
	v_cndmask_b32_e32 v78, 0, v74, vcc
	v_cndmask_b32_e32 v79, 0, v75, vcc
	v_lshl_add_u64 v[74:75], s[26:27], 0, v[88:89]
	v_lshl_add_u64 v[88:89], s[22:23], 0, v[90:91]
	v_cndmask_b32_e32 v80, 0, v76, vcc
	v_cndmask_b32_e32 v81, 0, v77, vcc
	v_cndmask_b32_e32 v76, 0, v92, vcc
	v_cndmask_b32_e32 v77, 0, v93, vcc
	v_cndmask_b32_e32 v86, 0, v86, vcc
	v_cndmask_b32_e32 v87, 0, v87, vcc
	v_lshl_add_u64 v[74:75], v[138:139], 1, v[74:75]
	v_lshl_add_u64 v[88:89], v[136:137], 2, v[88:89]
	s_and_saveexec_b64 s[2:3], s[18:19]
	s_cbranch_execz .LBB0_905
	global_load_dwordx2 v[80:81], v[74:75], off offset:768
	global_load_dwordx2 v[86:87], v[74:75], off offset:784
	global_load_dwordx4 v[76:79], v[88:89], off
	global_load_dwordx4 v[90:93], v[88:89], off offset:16
	s_waitcnt vmcnt(3)
	v_lshlrev_b32_e32 v83, 16, v81
	s_waitcnt vmcnt(2)
	v_lshlrev_b32_e32 v101, 16, v87
	s_waitcnt vmcnt(1)
	v_mov_b32_e32 v98, v77
	v_mov_b32_e32 v99, v79
	v_mov_b32_e32 v77, v78
	v_and_b32_e32 v79, 0xffff0000, v81
	v_and_b32_e32 v78, 0xffff0000, v87
	v_lshlrev_b32_e32 v96, 16, v86
	v_and_b32_e32 v97, 0xffff0000, v86
	s_waitcnt vmcnt(0)
	v_pk_mul_f32 v[104:105], v[92:93], v[78:79] op_sel:[0,1] op_sel_hi:[1,0]
	v_pk_mul_f32 v[78:79], v[92:93], v[78:79]
	v_lshlrev_b32_e32 v94, 16, v80
	v_and_b32_e32 v95, 0xffff0000, v80
	v_pk_mul_f32 v[80:81], v[76:77], v[96:97]
	v_pk_mul_f32 v[86:87], v[98:99], v[96:97]
	v_mul_f32_e32 v96, v90, v83
	v_mul_f32_e32 v100, v91, v101
	v_mul_f32_e32 v102, v91, v83
	v_mul_f32_e32 v90, v90, v101
	v_mov_b32_e32 v97, v104
	v_mov_b32_e32 v101, v105
	v_mov_b32_e32 v103, v79
	v_mov_b32_e32 v91, v78
	v_pk_fma_f32 v[76:77], v[76:77], v[94:95], v[86:87] neg_lo:[0,0,1] neg_hi:[0,0,1]
	v_pk_fma_f32 v[78:79], v[98:99], v[94:95], v[80:81]
	v_pk_add_f32 v[86:87], v[96:97], v[100:101] neg_lo:[0,1] neg_hi:[0,1]
	v_pk_add_f32 v[80:81], v[102:103], v[90:91]

; DI void rope4(f32x4& v0, f32x4& v1, const float* tab_row, int fq) {
;     const f32x4 cs0 = *(const f32x4*)(tab_row + 8 * fq), cs1 = *(const f32x4*)(tab_row + 8 * fq + 4);
;     const float c[4] = {cs0[0], cs0[2], cs1[0], cs1[2]}, s[4] = {cs0[1], cs0[3], cs1[1], cs1[3]};
;     f32x4 a, b;
; #pragma unroll
;     for (int j = 0; j < 4; ++j) { a[j] = v0[j] * c[j] - v1[j] * s[j]; b[j] = v0[j] * s[j] + v1[j] * c[j]; }
;     v0 = a; v1 = b;
; }
;     DI void operator()(const f32x4 (&acc)[2][2][4][2], const pg8::Unit& u, int wr, int wc, int fr, int fq) const {
;         asm volatile("" : "+v"(fr), "+v"(fq));
;         const int row0 = u.pm * 256 + wr * 64 + fr, col0 = wc * 32 + 8 * fq;
;         bf16_t* dst = u.pn == 0 ? Kb : Vb;
; #pragma unroll
;         for (int ai = 0; ai < 2; ++ai)
; #pragma unroll
;             for (int m = 0; m < 4; ++m) {
;                 const int row = row0 + ai * 128 + m * 16; const f32x4 p = *(const f32x4*)(SSQ + (size_t)row * 4);
;                 const float rs = __builtin_amdgcn_rsqf(((p[0] + p[1]) + (p[2] + p[3])) * (1.0f / 128.0f) + EPS);
; #pragma unroll
;                 for (int bj = 0; bj < 2; ++bj) { f32x4 v0 = acc[ai][bj][m][0] * rs, v1 = acc[ai][bj][m][1] * rs;
;                     if (u.pn == 0 && (wc & 1)) {
;                         if (fq < 2) { const u32x2 a = *(const u32x2*)(H + (size_t)row * HP + C_KR + 4 * fq), b = *(const u32x2*)(H + (size_t)row * HP + C_KR + 8 + 4 * fq);
;                             v0 = (f32x4){__uint_as_float(a.x << 16), __uint_as_float(a.x & 0xffff0000u), __uint_as_float(a.y << 16), __uint_as_float(a.y & 0xffff0000u)};
;                             v1 = (f32x4){__uint_as_float(b.x << 16), __uint_as_float(b.x & 0xffff0000u), __uint_as_float(b.y << 16), __uint_as_float(b.y & 0xffff0000u)};
;                             rope4(v0, v1, ROPE16 + (size_t)row * 16, fq); }
;                         else { v0 = (f32x4){0.f, 0.f, 0.f, 0.f}; v1 = v0; }
;                     }
;                     u32x4 w; w.x = pk2(v0[0], v0[1]); w.y = pk2(v0[2], v0[3]); w.z = pk2(v1[0], v1[1]); w.w = pk2(v1[2], v1[3]);
;                     *(u32x4*)(dst + (size_t)row * 256 + bj * 128 + col0) = w; }
;                 asm volatile("" ::: "memory");
;             }
;     }
.LBB0_907:
	s_or_b64 exec, exec, s[2:3]
	v_cvt_pk_bf16_f32 v68, v68, v69
	v_cvt_pk_bf16_f32 v69, v72, v73
	v_cvt_pk_bf16_f32 v70, v70, v71
	v_cvt_pk_bf16_f32 v71, v66, v67
	global_store_dwordx4 v[84:85], v[68:71], off offset:256
	s_nop 1
	v_add_u32_e32 v68, 0x80, v140
	v_ashrrev_i32_e32 v69, 31, v68
	v_lshl_add_u64 v[66:67], v[68:69], 4, s[28:29]
	s_nop 1
	v_mov_b32_e32 v70, v232
	v_mov_b32_e32 v71, v233
	v_mov_b32_e32 v72, v234
	v_mov_b32_e32 v73, v235
	v_lshlrev_b64 v[74:75], 6, v[68:69]
	s_nop 0
	v_mov_b32_e32 v66, v71
	v_mov_b32_e32 v67, v72
	v_mov_b32_e32 v71, v73
	v_pk_add_f32 v[66:67], v[66:67], v[70:71]
	v_mad_i64_i32 v[72:73], s[2:3], v68, s73, 0
	v_add_f32_e32 v66, v66, v67
	v_fmamk_f32 v66, v66, 0x3c000000, v202
	v_rsq_f32_e32 v66, v66
	s_nop 0
	v_pk_mul_f32 v[58:59], v[58:59], v[66:67] op_sel_hi:[1,0]
	v_pk_mul_f32 v[70:71], v[64:65], v[66:67] op_sel_hi:[1,0]
	v_pk_mul_f32 v[76:77], v[62:63], v[66:67] op_sel_hi:[1,0]
	v_pk_mul_f32 v[60:61], v[60:61], v[66:67] op_sel_hi:[1,0]
	v_cndmask_b32_e32 v62, 0, v58, vcc
	v_cndmask_b32_e32 v63, 0, v59, vcc
	v_lshl_add_u64 v[58:59], s[26:27], 0, v[72:73]
	v_lshl_add_u64 v[72:73], s[22:23], 0, v[74:75]
	v_cndmask_b32_e32 v64, 0, v60, vcc
	v_cndmask_b32_e32 v65, 0, v61, vcc
	v_cndmask_b32_e32 v60, 0, v76, vcc
	v_cndmask_b32_e32 v61, 0, v77, vcc
	v_cndmask_b32_e32 v70, 0, v70, vcc
	v_cndmask_b32_e32 v71, 0, v71, vcc
	v_lshl_add_u64 v[58:59], v[138:139], 1, v[58:59]
	v_lshl_add_u64 v[72:73], v[136:137], 2, v[72:73]
	s_and_saveexec_b64 s[2:3], s[18:19]
	s_cbranch_execz .LBB0_909
	global_load_dwordx2 v[64:65], v[58:59], off offset:768
	global_load_dwordx2 v[70:71], v[58:59], off offset:784
	global_load_dwordx4 v[60:63], v[72:73], off
	global_load_dwordx4 v[74:77], v[72:73], off offset:16
	s_waitcnt vmcnt(3)
	v_lshlrev_b32_e32 v67, 16, v65
	s_waitcnt vmcnt(2)
	v_lshlrev_b32_e32 v85, 16, v71
	s_waitcnt vmcnt(1)
	v_mov_b32_e32 v82, v61
	v_mov_b32_e32 v83, v63
	v_mov_b32_e32 v61, v62
	v_and_b32_e32 v63, 0xffff0000, v65
	v_and_b32_e32 v62, 0xffff0000, v71
	v_lshlrev_b32_e32 v80, 16, v70
	v_and_b32_e32 v81, 0xffff0000, v70
	s_waitcnt vmcnt(0)
	v_pk_mul_f32 v[88:89], v[76:77], v[62:63] op_sel:[0,1] op_sel_hi:[1,0]
	v_pk_mul_f32 v[62:63], v[76:77], v[62:63]
	v_lshlrev_b32_e32 v78, 16, v64
	v_and_b32_e32 v79, 0xffff0000, v64
	v_pk_mul_f32 v[64:65], v[60:61], v[80:81]
	v_pk_mul_f32 v[70:71], v[82:83], v[80:81]
	v_mul_f32_e32 v80, v74, v67
	v_mul_f32_e32 v84, v75, v85
	v_mul_f32_e32 v86, v75, v67
	v_mul_f32_e32 v74, v74, v85
	v_mov_b32_e32 v81, v88
	v_mov_b32_e32 v85, v89
	v_mov_b32_e32 v87, v63
	v_mov_b32_e32 v75, v62
	v_pk_fma_f32 v[60:61], v[60:61], v[78:79], v[70:71] neg_lo:[0,0,1] neg_hi:[0,0,1]
	v_pk_fma_f32 v[62:63], v[82:83], v[78:79], v[64:65]
	v_pk_add_f32 v[70:71], v[80:81], v[84:85] neg_lo:[0,1] neg_hi:[0,1]
	v_pk_add_f32 v[64:65], v[86:87], v[74:75]

; DI void rope4(f32x4& v0, f32x4& v1, const float* tab_row, int fq) {
;     const f32x4 cs0 = *(const f32x4*)(tab_row + 8 * fq), cs1 = *(const f32x4*)(tab_row + 8 * fq + 4);
;     const float c[4] = {cs0[0], cs0[2], cs1[0], cs1[2]}, s[4] = {cs0[1], cs0[3], cs1[1], cs1[3]};
;     f32x4 a, b;
; #pragma unroll
;     for (int j = 0; j < 4; ++j) { a[j] = v0[j] * c[j] - v1[j] * s[j]; b[j] = v0[j] * s[j] + v1[j] * c[j]; }
;     v0 = a; v1 = b;
; }
;     DI void operator()(const f32x4 (&acc)[2][2][4][2], const pg8::Unit& u, int wr, int wc, int fr, int fq) const {
;         asm volatile("" : "+v"(fr), "+v"(fq));
;         const int row0 = u.pm * 256 + wr * 64 + fr, col0 = wc * 32 + 8 * fq;
;         bf16_t* dst = u.pn == 0 ? Kb : Vb;
; #pragma unroll
;         for (int ai = 0; ai < 2; ++ai)
; #pragma unroll
;             for (int m = 0; m < 4; ++m) {
;                 const int row = row0 + ai * 128 + m * 16; const f32x4 p = *(const f32x4*)(SSQ + (size_t)row * 4);
;                 const float rs = __builtin_amdgcn_rsqf(((p[0] + p[1]) + (p[2] + p[3])) * (1.0f / 128.0f) + EPS);
; #pragma unroll
;                 for (int bj = 0; bj < 2; ++bj) { f32x4 v0 = acc[ai][bj][m][0] * rs, v1 = acc[ai][bj][m][1] * rs;
;                     if (u.pn == 0 && (wc & 1)) {
;                         if (fq < 2) { const u32x2 a = *(const u32x2*)(H + (size_t)row * HP + C_KR + 4 * fq), b = *(const u32x2*)(H + (size_t)row * HP + C_KR + 8 + 4 * fq);
;                             v0 = (f32x4){__uint_as_float(a.x << 16), __uint_as_float(a.x & 0xffff0000u), __uint_as_float(a.y << 16), __uint_as_float(a.y & 0xffff0000u)};
;                             v1 = (f32x4){__uint_as_float(b.x << 16), __uint_as_float(b.x & 0xffff0000u), __uint_as_float(b.y << 16), __uint_as_float(b.y & 0xffff0000u)};
;                             rope4(v0, v1, ROPE16 + (size_t)row * 16, fq); }
;                         else { v0 = (f32x4){0.f, 0.f, 0.f, 0.f}; v1 = v0; }
;                     }
;                     u32x4 w; w.x = pk2(v0[0], v0[1]); w.y = pk2(v0[2], v0[3]); w.z = pk2(v1[0], v1[1]); w.w = pk2(v1[2], v1[3]);
;                     *(u32x4*)(dst + (size_t)row * 256 + bj * 128 + col0) = w; }
;                 asm volatile("" ::: "memory");
;             }
;     }
.LBB0_911:
	s_or_b64 exec, exec, s[2:3]
	v_cvt_pk_bf16_f32 v52, v52, v53
	v_cvt_pk_bf16_f32 v53, v56, v57
	v_cvt_pk_bf16_f32 v54, v54, v55
	v_cvt_pk_bf16_f32 v55, v50, v51
	global_store_dwordx4 v[68:69], v[52:55], off offset:256
	s_nop 1
	v_add_u32_e32 v52, 0x90, v140
	v_ashrrev_i32_e32 v53, 31, v52
	v_lshl_add_u64 v[50:51], v[52:53], 4, s[28:29]
	s_nop 1
	v_mov_b32_e32 v54, v236
	v_mov_b32_e32 v55, v237
	v_mov_b32_e32 v56, v238
	v_mov_b32_e32 v57, v239
	v_lshlrev_b64 v[58:59], 6, v[52:53]
	s_nop 0
	v_mov_b32_e32 v50, v55
	v_mov_b32_e32 v51, v56
	v_mov_b32_e32 v55, v57
	v_pk_add_f32 v[50:51], v[50:51], v[54:55]
	v_mad_i64_i32 v[56:57], s[2:3], v52, s73, 0
	v_add_f32_e32 v50, v50, v51
	v_fmamk_f32 v50, v50, 0x3c000000, v202
	v_rsq_f32_e32 v50, v50
	s_nop 0
	v_pk_mul_f32 v[42:43], v[42:43], v[50:51] op_sel_hi:[1,0]
	v_pk_mul_f32 v[54:55], v[48:49], v[50:51] op_sel_hi:[1,0]
	v_pk_mul_f32 v[60:61], v[46:47], v[50:51] op_sel_hi:[1,0]
	v_pk_mul_f32 v[44:45], v[44:45], v[50:51] op_sel_hi:[1,0]
	v_cndmask_b32_e32 v46, 0, v42, vcc
	v_cndmask_b32_e32 v47, 0, v43, vcc
	v_lshl_add_u64 v[42:43], s[26:27], 0, v[56:57]
	v_lshl_add_u64 v[56:57], s[22:23], 0, v[58:59]
	v_cndmask_b32_e32 v48, 0, v44, vcc
	v_cndmask_b32_e32 v49, 0, v45, vcc
	v_cndmask_b32_e32 v44, 0, v60, vcc
	v_cndmask_b32_e32 v45, 0, v61, vcc
	v_cndmask_b32_e32 v54, 0, v54, vcc
	v_cndmask_b32_e32 v55, 0, v55, vcc
	v_lshl_add_u64 v[42:43], v[138:139], 1, v[42:43]
	v_lshl_add_u64 v[56:57], v[136:137], 2, v[56:57]
	s_and_saveexec_b64 s[2:3], s[18:19]
	s_cbranch_execz .LBB0_913
	global_load_dwordx2 v[48:49], v[42:43], off offset:768
	global_load_dwordx2 v[54:55], v[42:43], off offset:784
	global_load_dwordx4 v[44:47], v[56:57], off
	global_load_dwordx4 v[58:61], v[56:57], off offset:16
	s_waitcnt vmcnt(3)
	v_lshlrev_b32_e32 v51, 16, v49
	s_waitcnt vmcnt(2)
	v_lshlrev_b32_e32 v69, 16, v55
	s_waitcnt vmcnt(1)
	v_mov_b32_e32 v66, v45
	v_mov_b32_e32 v67, v47
	v_mov_b32_e32 v45, v46
	v_and_b32_e32 v47, 0xffff0000, v49
	v_and_b32_e32 v46, 0xffff0000, v55
	v_lshlrev_b32_e32 v64, 16, v54
	v_and_b32_e32 v65, 0xffff0000, v54
	s_waitcnt vmcnt(0)
	v_pk_mul_f32 v[72:73], v[60:61], v[46:47] op_sel:[0,1] op_sel_hi:[1,0]
	v_pk_mul_f32 v[46:47], v[60:61], v[46:47]
	v_lshlrev_b32_e32 v62, 16, v48
	v_and_b32_e32 v63, 0xffff0000, v48
	v_pk_mul_f32 v[48:49], v[44:45], v[64:65]
	v_pk_mul_f32 v[54:55], v[66:67], v[64:65]
	v_mul_f32_e32 v64, v58, v51
	v_mul_f32_e32 v68, v59, v69
	v_mul_f32_e32 v70, v59, v51
	v_mul_f32_e32 v58, v58, v69
	v_mov_b32_e32 v65, v72
	v_mov_b32_e32 v69, v73
	v_mov_b32_e32 v71, v47
	v_mov_b32_e32 v59, v46
	v_pk_fma_f32 v[44:45], v[44:45], v[62:63], v[54:55] neg_lo:[0,0,1] neg_hi:[0,0,1]
	v_pk_fma_f32 v[46:47], v[66:67], v[62:63], v[48:49]
	v_pk_add_f32 v[54:55], v[64:65], v[68:69] neg_lo:[0,1] neg_hi:[0,1]
	v_pk_add_f32 v[48:49], v[70:71], v[58:59]

; DI void rope4(f32x4& v0, f32x4& v1, const float* tab_row, int fq) {
;     const f32x4 cs0 = *(const f32x4*)(tab_row + 8 * fq), cs1 = *(const f32x4*)(tab_row + 8 * fq + 4);
;     const float c[4] = {cs0[0], cs0[2], cs1[0], cs1[2]}, s[4] = {cs0[1], cs0[3], cs1[1], cs1[3]};
;     f32x4 a, b;
; #pragma unroll
;     for (int j = 0; j < 4; ++j) { a[j] = v0[j] * c[j] - v1[j] * s[j]; b[j] = v0[j] * s[j] + v1[j] * c[j]; }
;     v0 = a; v1 = b;
; }
;     DI void operator()(const f32x4 (&acc)[2][2][4][2], const pg8::Unit& u, int wr, int wc, int fr, int fq) const {
;         asm volatile("" : "+v"(fr), "+v"(fq));
;         const int row0 = u.pm * 256 + wr * 64 + fr, col0 = wc * 32 + 8 * fq;
;         bf16_t* dst = u.pn == 0 ? Kb : Vb;
; #pragma unroll
;         for (int ai = 0; ai < 2; ++ai)
; #pragma unroll
;             for (int m = 0; m < 4; ++m) {
;                 const int row = row0 + ai * 128 + m * 16; const f32x4 p = *(const f32x4*)(SSQ + (size_t)row * 4);
;                 const float rs = __builtin_amdgcn_rsqf(((p[0] + p[1]) + (p[2] + p[3])) * (1.0f / 128.0f) + EPS);
; #pragma unroll
;                 for (int bj = 0; bj < 2; ++bj) { f32x4 v0 = acc[ai][bj][m][0] * rs, v1 = acc[ai][bj][m][1] * rs;
;                     if (u.pn == 0 && (wc & 1)) {
;                         if (fq < 2) { const u32x2 a = *(const u32x2*)(H + (size_t)row * HP + C_KR + 4 * fq), b = *(const u32x2*)(H + (size_t)row * HP + C_KR + 8 + 4 * fq);
;                             v0 = (f32x4){__uint_as_float(a.x << 16), __uint_as_float(a.x & 0xffff0000u), __uint_as_float(a.y << 16), __uint_as_float(a.y & 0xffff0000u)};
;                             v1 = (f32x4){__uint_as_float(b.x << 16), __uint_as_float(b.x & 0xffff0000u), __uint_as_float(b.y << 16), __uint_as_float(b.y & 0xffff0000u)};
;                             rope4(v0, v1, ROPE16 + (size_t)row * 16, fq); }
;                         else { v0 = (f32x4){0.f, 0.f, 0.f, 0.f}; v1 = v0; }
;                     }
;                     u32x4 w; w.x = pk2(v0[0], v0[1]); w.y = pk2(v0[2], v0[3]); w.z = pk2(v1[0], v1[1]); w.w = pk2(v1[2], v1[3]);
;                     *(u32x4*)(dst + (size_t)row * 256 + bj * 128 + col0) = w; }
;                 asm volatile("" ::: "memory");
;             }
;     }
.LBB0_915:
	s_or_b64 exec, exec, s[2:3]
	v_cvt_pk_bf16_f32 v36, v36, v37
	v_cvt_pk_bf16_f32 v37, v40, v41
	v_cvt_pk_bf16_f32 v38, v38, v39
	v_cvt_pk_bf16_f32 v39, v34, v35
	global_store_dwordx4 v[52:53], v[36:39], off offset:256
	s_nop 1
	v_add_u32_e32 v36, 0xa0, v140
	v_ashrrev_i32_e32 v37, 31, v36
	v_lshl_add_u64 v[34:35], v[36:37], 4, s[28:29]
	s_nop 1
	v_mov_b32_e32 v38, v240
	v_mov_b32_e32 v39, v241
	v_mov_b32_e32 v40, v242
	v_mov_b32_e32 v41, v243
	v_lshlrev_b64 v[42:43], 6, v[36:37]
	s_nop 0
	v_mov_b32_e32 v34, v39
	v_mov_b32_e32 v35, v40
	v_mov_b32_e32 v39, v41
	v_pk_add_f32 v[34:35], v[34:35], v[38:39]
	v_mad_i64_i32 v[40:41], s[2:3], v36, s73, 0
	v_add_f32_e32 v34, v34, v35
	v_fmamk_f32 v34, v34, 0x3c000000, v202
	v_rsq_f32_e32 v34, v34
	s_nop 0
	v_pk_mul_f32 v[26:27], v[26:27], v[34:35] op_sel_hi:[1,0]
	v_pk_mul_f32 v[38:39], v[32:33], v[34:35] op_sel_hi:[1,0]
	v_pk_mul_f32 v[44:45], v[30:31], v[34:35] op_sel_hi:[1,0]
	v_pk_mul_f32 v[28:29], v[28:29], v[34:35] op_sel_hi:[1,0]
	v_cndmask_b32_e32 v30, 0, v26, vcc
	v_cndmask_b32_e32 v31, 0, v27, vcc
	v_lshl_add_u64 v[26:27], s[26:27], 0, v[40:41]
	v_lshl_add_u64 v[40:41], s[22:23], 0, v[42:43]
	v_cndmask_b32_e32 v32, 0, v28, vcc
	v_cndmask_b32_e32 v33, 0, v29, vcc
	v_cndmask_b32_e32 v28, 0, v44, vcc
	v_cndmask_b32_e32 v29, 0, v45, vcc
	v_cndmask_b32_e32 v38, 0, v38, vcc
	v_cndmask_b32_e32 v39, 0, v39, vcc
	v_lshl_add_u64 v[26:27], v[138:139], 1, v[26:27]
	v_lshl_add_u64 v[40:41], v[136:137], 2, v[40:41]
	s_and_saveexec_b64 s[2:3], s[18:19]
	s_cbranch_execz .LBB0_917
	global_load_dwordx2 v[32:33], v[26:27], off offset:768
	global_load_dwordx2 v[38:39], v[26:27], off offset:784
	global_load_dwordx4 v[28:31], v[40:41], off
	global_load_dwordx4 v[42:45], v[40:41], off offset:16
	s_waitcnt vmcnt(3)
	v_lshlrev_b32_e32 v35, 16, v33
	s_waitcnt vmcnt(2)
	v_lshlrev_b32_e32 v53, 16, v39
	s_waitcnt vmcnt(1)
	v_mov_b32_e32 v50, v29
	v_mov_b32_e32 v51, v31
	v_mov_b32_e32 v29, v30
	v_and_b32_e32 v31, 0xffff0000, v33
	v_and_b32_e32 v30, 0xffff0000, v39
	v_lshlrev_b32_e32 v48, 16, v38
	v_and_b32_e32 v49, 0xffff0000, v38
	s_waitcnt vmcnt(0)
	v_pk_mul_f32 v[56:57], v[44:45], v[30:31] op_sel:[0,1] op_sel_hi:[1,0]
	v_pk_mul_f32 v[30:31], v[44:45], v[30:31]
	v_lshlrev_b32_e32 v46, 16, v32
	v_and_b32_e32 v47, 0xffff0000, v32
	v_pk_mul_f32 v[32:33], v[28:29], v[48:49]
	v_pk_mul_f32 v[38:39], v[50:51], v[48:49]
	v_mul_f32_e32 v48, v42, v35
	v_mul_f32_e32 v52, v43, v53
	v_mul_f32_e32 v54, v43, v35
	v_mul_f32_e32 v42, v42, v53
	v_mov_b32_e32 v49, v56
	v_mov_b32_e32 v53, v57
	v_mov_b32_e32 v55, v31
	v_mov_b32_e32 v43, v30
	v_pk_fma_f32 v[28:29], v[28:29], v[46:47], v[38:39] neg_lo:[0,0,1] neg_hi:[0,0,1]
	v_pk_fma_f32 v[30:31], v[50:51], v[46:47], v[32:33]
	v_pk_add_f32 v[38:39], v[48:49], v[52:53] neg_lo:[0,1] neg_hi:[0,1]
	v_pk_add_f32 v[32:33], v[54:55], v[42:43]

; DI void rope4(f32x4& v0, f32x4& v1, const float* tab_row, int fq) {
;     const f32x4 cs0 = *(const f32x4*)(tab_row + 8 * fq), cs1 = *(const f32x4*)(tab_row + 8 * fq + 4);
;     const float c[4] = {cs0[0], cs0[2], cs1[0], cs1[2]}, s[4] = {cs0[1], cs0[3], cs1[1], cs1[3]};
;     f32x4 a, b;
; #pragma unroll
;     for (int j = 0; j < 4; ++j) { a[j] = v0[j] * c[j] - v1[j] * s[j]; b[j] = v0[j] * s[j] + v1[j] * c[j]; }
;     v0 = a; v1 = b;
; }
;     DI void operator()(const f32x4 (&acc)[2][2][4][2], const pg8::Unit& u, int wr, int wc, int fr, int fq) const {
;         asm volatile("" : "+v"(fr), "+v"(fq));
;         const int row0 = u.pm * 256 + wr * 64 + fr, col0 = wc * 32 + 8 * fq;
;         bf16_t* dst = u.pn == 0 ? Kb : Vb;
; #pragma unroll
;         for (int ai = 0; ai < 2; ++ai)
; #pragma unroll
;             for (int m = 0; m < 4; ++m) {
;                 const int row = row0 + ai * 128 + m * 16; const f32x4 p = *(const f32x4*)(SSQ + (size_t)row * 4);
;                 const float rs = __builtin_amdgcn_rsqf(((p[0] + p[1]) + (p[2] + p[3])) * (1.0f / 128.0f) + EPS);
; #pragma unroll
;                 for (int bj = 0; bj < 2; ++bj) { f32x4 v0 = acc[ai][bj][m][0] * rs, v1 = acc[ai][bj][m][1] * rs;
;                     if (u.pn == 0 && (wc & 1)) {
;                         if (fq < 2) { const u32x2 a = *(const u32x2*)(H + (size_t)row * HP + C_KR + 4 * fq), b = *(const u32x2*)(H + (size_t)row * HP + C_KR + 8 + 4 * fq);
;                             v0 = (f32x4){__uint_as_float(a.x << 16), __uint_as_float(a.x & 0xffff0000u), __uint_as_float(a.y << 16), __uint_as_float(a.y & 0xffff0000u)};
;                             v1 = (f32x4){__uint_as_float(b.x << 16), __uint_as_float(b.x & 0xffff0000u), __uint_as_float(b.y << 16), __uint_as_float(b.y & 0xffff0000u)};
;                             rope4(v0, v1, ROPE16 + (size_t)row * 16, fq); }
;                         else { v0 = (f32x4){0.f, 0.f, 0.f, 0.f}; v1 = v0; }
;                     }
;                     u32x4 w; w.x = pk2(v0[0], v0[1]); w.y = pk2(v0[2], v0[3]); w.z = pk2(v1[0], v1[1]); w.w = pk2(v1[2], v1[3]);
;                     *(u32x4*)(dst + (size_t)row * 256 + bj * 128 + col0) = w; }
;                 asm volatile("" ::: "memory");
;             }
;     }
.LBB0_919:
	s_or_b64 exec, exec, s[2:3]
	v_cvt_pk_bf16_f32 v20, v20, v21
	v_cvt_pk_bf16_f32 v21, v24, v25
	v_cvt_pk_bf16_f32 v22, v22, v23
	v_cvt_pk_bf16_f32 v23, v18, v19
	v_add_u32_e32 v18, 0xb0, v140
	global_store_dwordx4 v[36:37], v[20:23], off offset:256
	v_ashrrev_i32_e32 v19, 31, v18
	v_mad_i64_i32 v[24:25], s[2:3], v18, s73, 0
	v_lshl_add_u64 v[20:21], v[18:19], 4, s[28:29]
	s_nop 1
	v_mov_b32_e32 v20, v244
	v_mov_b32_e32 v21, v245
	v_mov_b32_e32 v22, v246
	v_mov_b32_e32 v23, v247
	v_lshlrev_b64 v[26:27], 6, v[18:19]
	s_nop 0
	v_mov_b32_e32 v28, v21
	v_mov_b32_e32 v29, v22
	v_mov_b32_e32 v21, v23
	v_pk_add_f32 v[20:21], v[28:29], v[20:21]
	v_lshl_add_u64 v[28:29], s[22:23], 0, v[26:27]
	v_add_f32_e32 v20, v20, v21
	v_fmamk_f32 v20, v20, 0x3c000000, v202
	v_rsq_f32_e32 v22, v20
	v_lshl_add_u64 v[20:21], s[26:27], 0, v[24:25]
	v_lshl_add_u64 v[20:21], v[138:139], 1, v[20:21]
	v_pk_mul_f32 v[26:27], v[16:17], v[22:23] op_sel_hi:[1,0]
	v_pk_mul_f32 v[14:15], v[14:15], v[22:23] op_sel_hi:[1,0]
	v_pk_mul_f32 v[12:13], v[12:13], v[22:23] op_sel_hi:[1,0]
	v_pk_mul_f32 v[10:11], v[10:11], v[22:23] op_sel_hi:[1,0]
	v_cndmask_b32_e32 v24, 0, v12, vcc
	v_cndmask_b32_e32 v16, 0, v10, vcc
	v_cndmask_b32_e32 v17, 0, v11, vcc
	v_cndmask_b32_e32 v25, 0, v13, vcc
	v_cndmask_b32_e32 v14, 0, v14, vcc
	v_cndmask_b32_e32 v15, 0, v15, vcc
	v_cndmask_b32_e32 v26, 0, v26, vcc
	v_cndmask_b32_e32 v27, 0, v27, vcc
	v_lshl_add_u64 v[10:11], v[136:137], 2, v[28:29]
	s_and_saveexec_b64 s[2:3], s[18:19]
	s_cbranch_execz .LBB0_921
	global_load_dwordx2 v[16:17], v[20:21], off offset:768
	global_load_dwordx2 v[28:29], v[20:21], off offset:784
	global_load_dwordx4 v[12:15], v[10:11], off
	global_load_dwordx4 v[24:27], v[10:11], off offset:16
	s_waitcnt vmcnt(3)
	v_lshlrev_b32_e32 v23, 16, v17
	s_waitcnt vmcnt(2)
	v_lshlrev_b32_e32 v37, 16, v29
	s_waitcnt vmcnt(1)
	v_mov_b32_e32 v34, v13
	v_mov_b32_e32 v35, v15
	v_mov_b32_e32 v13, v14
	v_and_b32_e32 v15, 0xffff0000, v17
	v_and_b32_e32 v14, 0xffff0000, v29
	v_lshlrev_b32_e32 v32, 16, v28
	v_and_b32_e32 v33, 0xffff0000, v28
	s_waitcnt vmcnt(0)
	v_pk_mul_f32 v[40:41], v[26:27], v[14:15] op_sel:[0,1] op_sel_hi:[1,0]
	v_pk_mul_f32 v[26:27], v[26:27], v[14:15]
	v_lshlrev_b32_e32 v30, 16, v16
	v_and_b32_e32 v31, 0xffff0000, v16
	v_pk_mul_f32 v[16:17], v[12:13], v[32:33]
	v_pk_mul_f32 v[28:29], v[34:35], v[32:33]
	v_mul_f32_e32 v32, v24, v23
	v_mul_f32_e32 v36, v25, v37
	v_mul_f32_e32 v38, v25, v23
	v_mul_f32_e32 v24, v24, v37
	v_mov_b32_e32 v33, v40
	v_mov_b32_e32 v37, v41
	v_mov_b32_e32 v39, v27
	v_mov_b32_e32 v25, v26
	v_pk_fma_f32 v[14:15], v[12:13], v[30:31], v[28:29] neg_lo:[0,0,1] neg_hi:[0,0,1]
	v_pk_fma_f32 v[16:17], v[34:35], v[30:31], v[16:17]
	v_pk_add_f32 v[26:27], v[32:33], v[36:37] neg_lo:[0,1] neg_hi:[0,1]
	v_pk_add_f32 v[24:25], v[38:39], v[24:25]
